# grid barrier: the first workgroup of each XCD to arrive issues an early background L2 write-back (leader still flushes at the end)
# baseline (speedup 1.0000x reference)
.LBB0_1326:
	s_waitcnt lgkmcnt(0)
	s_nop 0
	v_readfirstlane_b32 s2, v4
	v_readfirstlane_b32 s3, v2
	v_readlane_b32 s4, v254, 1
	s_lshl_b32 s0, s0, 8
	s_add_u32 s10, s38, s0
	s_addc_u32 s11, s39, 0
	s_add_u32 s12, s10, 0x1400
	s_addc_u32 s13, s11, 0
	s_add_i32 s5, s4, 1
	v_writelane_b32 v254, s5, 1
	s_mul_i32 s6, s5, s2
	s_mul_i32 s7, s5, s3
	v_mov_b32_e32 v5, 0
	global_atomic_add v6, v5, v228, s[12:13] sc0
	s_add_u32 s12, s10, 0x2400
	s_addc_u32 s13, s11, 0
	s_waitcnt vmcnt(0)
	v_readfirstlane_b32 s8, v6
	s_add_i32 s8, s8, 1
	s_sub_i32 s99, s6, s2
	s_add_i32 s99, s99, 1
	s_cmp_eq_u32 s8, s99
	s_cbranch_scc0 .Lxb_notfirst
	buffer_wbl2 sc1
.Lxb_notfirst:
	s_cmp_eq_u32 s8, s6
	s_cbranch_scc1 .Lxb_leader
	s_mov_b32 s9, 0
